# v8 + all six GEMM prologues issue the K-tile-1 stages before the first prologue wait (vmcnt(2)->vmcnt(8) after 14 DMAs)
# speedup vs baseline: 1.0036x; 1.0003x over previous
.LBB0_140:
	s_lshl_b32 s7, s7, 5
	s_and_b32 s14, s7, 0x60
	s_lshl_b32 s9, s8, 13
	s_lshl_b32 s7, s14, 7
	s_add_u32 s12, s34, 0x8000
	v_readlane_b32 s40, v253, 38
	s_addc_u32 s13, s35, 0
	v_mov_b32_e32 v133, v3
	v_mov_b32_e32 v137, v3
	v_readlane_b32 s41, v253, 39
	s_add_i32 m0, s47, 0x18000
	v_lshl_add_u64 v[16:17], s[12:13], 0, v[2:3]
	v_lshl_add_u64 v[12:13], s[40:41], 0, v[136:137]
	v_mov_b32_e32 v135, v3
	global_load_lds_dwordx4 v[16:17], off
	v_lshl_add_u64 v[16:17], s[12:13], 0, v[132:133]
	s_add_i32 m0, s47, 0x1a000
	s_add_i32 s51, s47, 0x8000
	s_add_i32 s52, s47, 0xa000
	v_lshl_add_u64 v[14:15], s[40:41], 0, v[134:135]
	global_load_lds_dwordx4 v[16:17], off
	v_lshl_add_u64 v[12:13], v[12:13], 0, s[4:5]
	s_mov_b32 m0, s51
	s_add_u32 s12, s34, 0xc000
	global_load_lds_dwordx4 v[12:13], off
	v_lshl_add_u64 v[12:13], v[14:15], 0, s[4:5]
	s_mov_b32 m0, s52
	s_addc_u32 s13, s35, 0
	global_load_lds_dwordx4 v[12:13], off
	s_add_i32 m0, s47, 0x1c000
	v_lshl_add_u64 v[12:13], s[12:13], 0, v[2:3]
	global_load_lds_dwordx4 v[12:13], off
	v_lshl_add_u64 v[12:13], s[12:13], 0, v[132:133]
	s_add_i32 m0, s47, 0x1e000
	v_and_b32_e32 v11, 15, v5
	global_load_lds_dwordx4 v[12:13], off
	s_waitcnt vmcnt(8)
	s_barrier
	v_lshrrev_b32_e32 v5, 1, v5
	v_and_b32_e32 v5, 24, v5
	v_lshlrev_b32_e32 v12, 1, v5
	v_or_b32_e32 v146, s14, v5
	v_lshlrev_b32_e32 v5, 15, v9
	v_and_b32_e32 v5, 0xffff0000, v5
	v_lshl_or_b32 v142, s8, 6, v11
	v_lshl_or_b32 v12, v11, 6, v12
	v_lshlrev_b32_e32 v11, 2, v11
	v_lshl_add_u32 v5, v8, 12, v5
	v_and_b32_e32 v8, 1, v9
	v_and_b32_e32 v13, 32, v11
	s_cmpk_lt_u32 s6, 0x100
	v_lshl_or_b32 v5, v8, 6, v5
	v_bitop3_b32 v143, v12, s7, v13 bitop3:0xde
	s_cselect_b64 s[6:7], -1, 0
	s_lshl_b32 s8, s8, 8
	v_lshl_add_u32 v138, v10, 1, v5
	v_lshlrev_b32_e32 v5, 15, v4
	s_add_i32 s8, s8, 0
	v_and_b32_e32 v5, 0xffff0000, v5
	v_bitop3_b32 v14, v12, s9, v13 bitop3:0xde
	s_waitcnt vmcnt(6)
	s_add_i32 s9, s8, 0x20400
	s_add_i32 s8, s8, 0x20600
	v_lshl_add_u32 v5, v6, 12, v5
	v_and_b32_e32 v4, 1, v4
	v_add_u32_e32 v144, s9, v11
	v_add_u32_e32 v145, s8, v11
	v_lshl_or_b32 v4, v4, 6, v5
	v_readlane_b32 s8, v253, 36
	v_mov_b32_e32 v139, v3
	v_lshl_add_u32 v140, v7, 1, v4
	v_mov_b32_e32 v141, v3
	s_mov_b32 s53, 0
	v_add_u32_e32 v147, 0, v14
	v_readlane_b32 s54, v253, 33
	s_mov_b32 s55, s8
	s_barrier
	v_readlane_b32 s9, v253, 37
	s_branch .LBB0_143

.LBB0_209:
	v_bfe_u32 v18, v12, 4, 2
	v_and_b32_e32 v13, 15, v12
	v_lshlrev_b32_e32 v251, 4, v18
	v_lshlrev_b32_e32 v12, 2, v12
	s_and_b32 s12, s8, 3
	v_lshl_or_b32 v197, s7, 6, v13
	v_lshl_or_b32 v13, v13, 6, v251
	s_lshl_b32 s7, s7, 13
	v_and_b32_e32 v12, 32, v12
	v_bitop3_b32 v20, v13, s7, v12 bitop3:0xde
	s_lshl_b32 s7, s12, 12
	s_add_u32 s8, s22, 0x8000
	v_readlane_b32 s14, v253, 43
	s_addc_u32 s9, s23, 0
	v_mov_b32_e32 v215, v3
	v_mov_b32_e32 v219, v3
	v_readlane_b32 s15, v253, 44
	v_bitop3_b32 v202, v13, s7, v12 bitop3:0xde
	s_add_i32 m0, s53, 0x18000
	v_lshl_add_u64 v[12:13], s[8:9], 0, v[2:3]
	v_lshl_add_u64 v[14:15], s[14:15], 0, v[218:219]
	v_mov_b32_e32 v217, v3
	global_load_lds_dwordx4 v[12:13], off
	v_lshl_add_u64 v[12:13], s[8:9], 0, v[214:215]
	s_add_i32 m0, s53, 0x1a000
	s_add_i32 s57, s53, 0x8000
	s_add_i32 s58, s53, 0xa000
	v_lshl_add_u64 v[16:17], s[14:15], 0, v[216:217]
	global_load_lds_dwordx4 v[12:13], off
	v_lshl_add_u64 v[12:13], v[14:15], 0, s[4:5]
	s_mov_b32 m0, s57
	s_add_u32 s8, s22, 0xc000
	global_load_lds_dwordx4 v[12:13], off
	v_lshl_add_u64 v[12:13], v[16:17], 0, s[4:5]
	s_mov_b32 m0, s58
	s_addc_u32 s9, s23, 0
	global_load_lds_dwordx4 v[12:13], off
	s_add_i32 m0, s53, 0x1c000
	v_lshl_add_u64 v[12:13], s[8:9], 0, v[2:3]
	global_load_lds_dwordx4 v[12:13], off
	v_lshl_add_u64 v[12:13], s[8:9], 0, v[214:215]
	s_add_i32 m0, s53, 0x1e000
	s_movk_i32 s34, 0x1600
	global_load_lds_dwordx4 v[12:13], off
	s_waitcnt vmcnt(8)
	s_barrier
	v_lshrrev_b32_e32 v9, 1, v9
	v_mul_lo_u32 v8, v8, s34
	s_mov_b32 s13, 0x16000
	v_mad_u64_u32 v[8:9], s[8:9], v9, s13, v[8:9]
	v_or_b32_e32 v8, v8, v10
	v_add_lshl_u32 v8, v8, v11, 1
	v_mov_b32_e32 v9, v3
	s_mov_b64 s[46:47], 0x160080
	v_lshl_add_u64 v[220:221], v[8:9], 0, s[46:47]
	v_lshrrev_b32_e32 v8, 1, v4
	v_mul_lo_u32 v4, v5, s34
	v_mad_u64_u32 v[4:5], s[8:9], v8, s13, v[4:5]
	s_waitcnt vmcnt(6)
	v_or_b32_e32 v4, v4, v6
	v_lshlrev_b32_e32 v19, 3, v18
	s_cmpk_lt_u32 s6, 0x100
	v_add_lshl_u32 v4, v4, v7, 1
	v_mov_b32_e32 v5, v3
	v_readlane_b32 s8, v254, 4
	v_lshl_or_b32 v203, s12, 5, v19
	s_cselect_b64 s[6:7], -1, 0
	s_mov_b32 s59, 0
	v_cmp_eq_u32_e64 s[38:39], 0, v18
	v_cmp_eq_u32_e64 s[40:41], 1, v18
	v_cmp_eq_u32_e64 s[42:43], 2, v18
	v_cmp_eq_u32_e64 s[44:45], 3, v18
	v_lshl_add_u64 v[222:223], v[4:5], 0, s[46:47]
	v_add_u32_e32 v204, 0, v20
	s_lshl_b32 s94, s12, 2
	v_readlane_b32 s62, v253, 42
	s_mov_b32 s63, s8
	s_barrier
	v_readlane_b32 s9, v254, 5
	s_branch .LBB0_212

.LBB0_304:
	v_and_b32_e32 v11, 15, v10
	v_bfe_u32 v10, v10, 4, 2
	v_lshlrev_b32_e32 v16, 3, v10
	v_lshlrev_b32_e32 v10, 4, v10
	v_lshlrev_b32_e32 v17, 2, v11
	s_and_b32 s7, s7, 3
	v_lshl_or_b32 v146, s8, 6, v11
	v_lshl_or_b32 v10, v11, 6, v10
	s_lshl_b32 s9, s8, 13
	v_and_b32_e32 v11, 32, v17
	v_bitop3_b32 v18, v10, s9, v11 bitop3:0xde
	s_lshl_b32 s9, s7, 12
	s_add_u32 s12, s34, 0x8000
	v_readlane_b32 s40, v253, 52
	s_addc_u32 s13, s35, 0
	v_mov_b32_e32 v133, v3
	v_mov_b32_e32 v137, v3
	v_readlane_b32 s41, v253, 53
	v_bitop3_b32 v147, v10, s9, v11 bitop3:0xde
	s_add_i32 m0, s45, 0x18000
	v_lshl_add_u64 v[10:11], s[12:13], 0, v[2:3]
	v_lshl_add_u64 v[12:13], s[40:41], 0, v[136:137]
	v_mov_b32_e32 v135, v3
	global_load_lds_dwordx4 v[10:11], off
	v_lshl_add_u64 v[10:11], s[12:13], 0, v[132:133]
	s_add_i32 m0, s45, 0x1a000
	s_add_i32 s49, s45, 0x8000
	s_add_i32 s50, s45, 0xa000
	v_lshl_add_u64 v[14:15], s[40:41], 0, v[134:135]
	global_load_lds_dwordx4 v[10:11], off
	v_lshl_add_u64 v[10:11], v[12:13], 0, s[4:5]
	s_mov_b32 m0, s49
	s_add_u32 s12, s34, 0xc000
	global_load_lds_dwordx4 v[10:11], off
	v_lshl_add_u64 v[10:11], v[14:15], 0, s[4:5]
	s_mov_b32 m0, s50
	s_addc_u32 s13, s35, 0
	global_load_lds_dwordx4 v[10:11], off
	s_add_i32 m0, s45, 0x1c000
	v_lshl_add_u64 v[10:11], s[12:13], 0, v[2:3]
	global_load_lds_dwordx4 v[10:11], off
	v_lshl_add_u64 v[10:11], s[12:13], 0, v[132:133]
	s_add_i32 m0, s45, 0x1e000
	s_cmpk_lt_u32 s6, 0x100
	global_load_lds_dwordx4 v[10:11], off
	s_waitcnt vmcnt(8)
	s_barrier
	v_lshlrev_b32_e32 v10, 15, v8
	v_and_b32_e32 v10, 0xffff0000, v10
	v_lshl_add_u32 v7, v7, 12, v10
	v_and_b32_e32 v8, 1, v8
	v_lshl_or_b32 v7, v8, 6, v7
	v_lshl_or_b32 v148, s7, 5, v16
	s_cselect_b64 s[6:7], -1, 0
	s_lshl_b32 s8, s8, 8
	v_lshl_add_u32 v138, v9, 1, v7
	v_lshlrev_b32_e32 v7, 15, v4
	s_add_i32 s8, s8, 0
	v_and_b32_e32 v7, 0xffff0000, v7
	s_waitcnt vmcnt(6)
	s_add_i32 s9, s8, 0x20400
	s_add_i32 s8, s8, 0x20600
	v_lshl_add_u32 v5, v5, 12, v7
	v_and_b32_e32 v4, 1, v4
	v_add_u32_e32 v149, s9, v17
	v_add_u32_e32 v150, s8, v17
	v_lshl_or_b32 v4, v4, 6, v5
	v_readlane_b32 s8, v253, 50
	v_mov_b32_e32 v139, v3
	v_lshl_add_u32 v140, v6, 1, v4
	v_mov_b32_e32 v141, v3
	s_mov_b32 s51, 0
	v_add_u32_e32 v151, 0, v18
	v_readlane_b32 s52, v253, 47
	s_mov_b32 s53, s8
	s_barrier
	v_readlane_b32 s9, v253, 51
	s_branch .LBB0_334

.LBB0_320:
	v_and_b32_e32 v11, 15, v10
	v_bfe_u32 v10, v10, 4, 2
	v_lshlrev_b32_e32 v16, 3, v10
	v_lshlrev_b32_e32 v10, 4, v10
	v_lshlrev_b32_e32 v17, 2, v11
	s_and_b32 s7, s7, 3
	v_lshl_or_b32 v146, s8, 6, v11
	v_lshl_or_b32 v10, v11, 6, v10
	s_lshl_b32 s9, s8, 13
	v_and_b32_e32 v11, 32, v17
	v_bitop3_b32 v18, v10, s9, v11 bitop3:0xde
	s_lshl_b32 s9, s7, 12
	s_add_u32 s12, s34, 0x8000
	v_readlane_b32 s40, v253, 62
	s_addc_u32 s13, s35, 0
	v_mov_b32_e32 v133, v3
	v_mov_b32_e32 v137, v3
	v_readlane_b32 s41, v253, 63
	v_bitop3_b32 v147, v10, s9, v11 bitop3:0xde
	s_add_i32 m0, s45, 0x18000
	v_lshl_add_u64 v[10:11], s[12:13], 0, v[2:3]
	v_lshl_add_u64 v[12:13], s[40:41], 0, v[136:137]
	v_mov_b32_e32 v135, v3
	global_load_lds_dwordx4 v[10:11], off
	v_lshl_add_u64 v[10:11], s[12:13], 0, v[132:133]
	s_add_i32 m0, s45, 0x1a000
	s_add_i32 s49, s45, 0x8000
	s_add_i32 s50, s45, 0xa000
	v_lshl_add_u64 v[14:15], s[40:41], 0, v[134:135]
	global_load_lds_dwordx4 v[10:11], off
	v_lshl_add_u64 v[10:11], v[12:13], 0, s[4:5]
	s_mov_b32 m0, s49
	s_add_u32 s12, s34, 0xc000
	global_load_lds_dwordx4 v[10:11], off
	v_lshl_add_u64 v[10:11], v[14:15], 0, s[4:5]
	s_mov_b32 m0, s50
	s_addc_u32 s13, s35, 0
	global_load_lds_dwordx4 v[10:11], off
	s_add_i32 m0, s45, 0x1c000
	v_lshl_add_u64 v[10:11], s[12:13], 0, v[2:3]
	global_load_lds_dwordx4 v[10:11], off
	v_lshl_add_u64 v[10:11], s[12:13], 0, v[132:133]
	s_add_i32 m0, s45, 0x1e000
	s_cmpk_lt_u32 s6, 0x100
	global_load_lds_dwordx4 v[10:11], off
	s_waitcnt vmcnt(8)
	s_barrier
	v_lshlrev_b32_e32 v10, 15, v8
	v_and_b32_e32 v10, 0xffff0000, v10
	v_lshl_add_u32 v7, v7, 12, v10
	v_and_b32_e32 v8, 1, v8
	v_lshl_or_b32 v7, v8, 6, v7
	v_lshl_or_b32 v148, s7, 5, v16
	s_cselect_b64 s[6:7], -1, 0
	s_lshl_b32 s8, s8, 8
	v_lshl_add_u32 v138, v9, 1, v7
	v_lshlrev_b32_e32 v7, 15, v4
	s_add_i32 s8, s8, 0
	v_and_b32_e32 v7, 0xffff0000, v7
	s_waitcnt vmcnt(6)
	s_add_i32 s9, s8, 0x20400
	s_add_i32 s8, s8, 0x20600
	v_lshl_add_u32 v5, v5, 12, v7
	v_and_b32_e32 v4, 1, v4
	v_add_u32_e32 v149, s9, v17
	v_add_u32_e32 v150, s8, v17
	v_lshl_or_b32 v4, v4, 6, v5
	v_readlane_b32 s8, v253, 60
	v_mov_b32_e32 v139, v3
	v_lshl_add_u32 v140, v6, 1, v4
	v_mov_b32_e32 v141, v3
	s_mov_b32 s51, 0
	v_add_u32_e32 v151, 0, v18
	v_readlane_b32 s52, v253, 56
	s_mov_b32 s53, s8
	s_barrier
	v_readlane_b32 s9, v253, 61
	s_branch .LBB0_323

.LBB0_356:
	v_and_b32_e32 v11, 15, v10
	v_bfe_u32 v16, v10, 4, 2
	v_lshlrev_b32_e32 v10, 4, v16
	v_lshlrev_b32_e32 v18, 2, v11
	s_and_b32 s23, s8, 3
	v_lshl_or_b32 v149, s6, 6, v11
	v_lshl_or_b32 v10, v11, 6, v10
	s_lshl_b32 s8, s6, 13
	v_and_b32_e32 v11, 32, v18
	v_bitop3_b32 v19, v10, s8, v11 bitop3:0xde
	s_lshl_b32 s8, s23, 12
	v_bitop3_b32 v150, v10, s8, v11 bitop3:0xde
	s_add_u32 s8, s0, 0x8000
	v_readlane_b32 s40, v254, 14
	s_addc_u32 s9, s1, 0
	v_mov_b32_e32 v133, v3
	v_mov_b32_e32 v137, v3
	v_readlane_b32 s41, v254, 15
	s_add_i32 m0, s13, 0x18000
	v_lshl_add_u64 v[10:11], s[8:9], 0, v[2:3]
	v_lshl_add_u64 v[12:13], s[40:41], 0, v[136:137]
	v_mov_b32_e32 v135, v3
	global_load_lds_dwordx4 v[10:11], off
	v_lshl_add_u64 v[10:11], s[8:9], 0, v[132:133]
	s_add_i32 m0, s13, 0x1a000
	s_add_i32 s34, s13, 0x8000
	s_add_i32 s35, s13, 0xa000
	v_lshl_add_u64 v[14:15], s[40:41], 0, v[134:135]
	global_load_lds_dwordx4 v[10:11], off
	v_lshl_add_u64 v[10:11], v[12:13], 0, s[4:5]
	s_mov_b32 m0, s34
	s_add_u32 s8, s0, 0xc000
	global_load_lds_dwordx4 v[10:11], off
	v_lshl_add_u64 v[10:11], v[14:15], 0, s[4:5]
	s_mov_b32 m0, s35
	s_addc_u32 s9, s1, 0
	global_load_lds_dwordx4 v[10:11], off
	s_add_i32 m0, s13, 0x1c000
	v_lshl_add_u64 v[10:11], s[8:9], 0, v[2:3]
	global_load_lds_dwordx4 v[10:11], off
	v_lshl_add_u64 v[10:11], s[8:9], 0, v[132:133]
	s_add_i32 m0, s13, 0x1e000
	s_cmpk_lt_u32 s7, 0x100
	global_load_lds_dwordx4 v[10:11], off
	s_waitcnt vmcnt(8)
	s_barrier
	v_lshlrev_b32_e32 v10, 15, v8
	v_and_b32_e32 v10, 0xffff0000, v10
	v_lshl_add_u32 v7, v7, 12, v10
	v_and_b32_e32 v8, 1, v8
	s_cselect_b64 s[46:47], -1, 0
	s_lshl_b32 s6, s6, 8
	v_lshl_or_b32 v7, v8, 6, v7
	s_add_i32 s6, s6, 0
	v_lshl_add_u32 v138, v9, 1, v7
	v_lshlrev_b32_e32 v7, 15, v4
	s_add_i32 s7, s6, 0x20400
	s_add_i32 s6, s6, 0x20600
	v_and_b32_e32 v7, 0xffff0000, v7
	s_waitcnt vmcnt(6)
	v_add_u32_e32 v152, s7, v18
	v_add_u32_e32 v153, s6, v18
	v_lshl_add_u32 v5, v5, 12, v7
	v_and_b32_e32 v4, 1, v4
	v_readlane_b32 s6, v254, 12
	v_lshlrev_b32_e32 v17, 3, v16
	v_lshl_or_b32 v4, v4, 6, v5
	v_readlane_b32 s7, v254, 13
	v_lshl_or_b32 v151, s23, 5, v17
	s_mov_b32 s56, 0
	v_cmp_eq_u32_e64 s[38:39], 0, v16
	v_mov_b32_e32 v139, v3
	v_lshl_add_u32 v140, v6, 1, v4
	v_mov_b32_e32 v141, v3
	v_add_u32_e32 v154, 0, v19
	v_readlane_b32 s57, v253, 59
	s_mov_b32 s42, s6
	s_mov_b64 s[6:7], s[40:41]
	s_barrier
	s_branch .LBB0_359

.LBB0_723:
	v_bfe_u32 v16, v10, 4, 2
	v_and_b32_e32 v11, 15, v10
	v_lshlrev_b32_e32 v203, 4, v16
	v_lshlrev_b32_e32 v10, 2, v10
	s_and_b32 s12, s8, 3
	v_lshl_or_b32 v202, s7, 6, v11
	v_lshl_or_b32 v11, v11, 6, v203
	s_lshl_b32 s7, s7, 13
	v_and_b32_e32 v10, 32, v10
	v_bitop3_b32 v18, v11, s7, v10 bitop3:0xde
	s_lshl_b32 s7, s12, 12
	s_add_u32 s8, s34, 0x8000
	v_readlane_b32 s48, v254, 6
	s_addc_u32 s9, s35, 0
	v_mov_b32_e32 v197, v3
	v_mov_b32_e32 v217, v3
	v_readlane_b32 s49, v254, 7
	v_bitop3_b32 v204, v11, s7, v10 bitop3:0xde
	s_add_i32 m0, s55, 0x18000
	v_lshl_add_u64 v[10:11], s[8:9], 0, v[2:3]
	v_lshl_add_u64 v[12:13], s[48:49], 0, v[216:217]
	v_mov_b32_e32 v215, v3
	global_load_lds_dwordx4 v[10:11], off
	v_lshl_add_u64 v[10:11], s[8:9], 0, v[196:197]
	s_add_i32 m0, s55, 0x1a000
	s_add_i32 s59, s55, 0x8000
	s_add_i32 s60, s55, 0xa000
	v_lshl_add_u64 v[14:15], s[48:49], 0, v[214:215]
	global_load_lds_dwordx4 v[10:11], off
	v_lshl_add_u64 v[10:11], v[12:13], 0, s[4:5]
	s_mov_b32 m0, s59
	s_add_u32 s8, s34, 0xc000
	global_load_lds_dwordx4 v[10:11], off
	v_lshl_add_u64 v[10:11], v[14:15], 0, s[4:5]
	s_mov_b32 m0, s60
	s_addc_u32 s9, s35, 0
	global_load_lds_dwordx4 v[10:11], off
	s_add_i32 m0, s55, 0x1c000
	v_lshl_add_u64 v[10:11], s[8:9], 0, v[2:3]
	global_load_lds_dwordx4 v[10:11], off
	v_lshl_add_u64 v[10:11], s[8:9], 0, v[196:197]
	s_add_i32 m0, s55, 0x1e000
	v_lshlrev_b32_e32 v17, 3, v16
	global_load_lds_dwordx4 v[10:11], off
	s_waitcnt vmcnt(8)
	s_barrier
	v_lshlrev_b32_e32 v10, 15, v8
	v_and_b32_e32 v10, 0xffff0000, v10
	v_lshl_add_u32 v7, v7, 12, v10
	v_and_b32_e32 v8, 1, v8
	v_lshl_or_b32 v7, v8, 6, v7
	v_lshl_add_u32 v218, v9, 1, v7
	v_lshlrev_b32_e32 v7, 15, v4
	v_and_b32_e32 v7, 0xffff0000, v7
	s_waitcnt vmcnt(6)
	v_lshl_add_u32 v5, v5, 12, v7
	v_and_b32_e32 v4, 1, v4
	s_cmpk_lt_u32 s6, 0x100
	v_lshl_or_b32 v4, v4, 6, v5
	v_readlane_b32 s8, v254, 4
	v_lshl_or_b32 v205, s12, 5, v17
	s_cselect_b64 s[6:7], -1, 0
	s_mov_b32 s61, 0
	v_cmp_eq_u32_e64 s[38:39], 0, v16
	v_cmp_eq_u32_e64 s[40:41], 1, v16
	v_cmp_eq_u32_e64 s[42:43], 2, v16
	v_cmp_eq_u32_e64 s[44:45], 3, v16
	v_mov_b32_e32 v219, v3
	v_lshl_add_u32 v220, v6, 1, v4
	v_mov_b32_e32 v221, v3
	v_add_u32_e32 v244, 0, v18
	s_lshl_b32 s94, s12, 2
	v_readlane_b32 s62, v253, 42
	s_mov_b32 s63, s8
	s_barrier
	v_readlane_b32 s9, v254, 5
	s_branch .LBB0_726
